# attention epilogue: 1/l computed once per row before the LDS exchange (15 fewer v_rcp per lane per unit); on top of the 64 B loop-head alignment
# baseline (speedup 1.0000x reference)
.LBB0_1417:
	v_rcp_f32_e32 v43, v43
	v_cmp_gt_u32_e32 vcc, 32, v188
	s_and_saveexec_b64 s[2:3], vcc
	v_lshl_add_u32 v44, v188, 2, s97
	ds_write_b32 v44, v43 offset:128
	s_or_b64 exec, exec, s[2:3]
	s_waitcnt lgkmcnt(0)
	ds_read_b128 v[44:47], v196 offset:128
	v_mov_b32_e32 v48, v80
	v_mov_b32_e32 v49, v96
	v_lshlrev_b32_e32 v43, 1, v193
	v_mov_b32_e32 v96, v81
	s_waitcnt lgkmcnt(0)
	s_waitcnt vmcnt(3)
	v_lshlrev_b32_e32 v50, 16, v36
	v_and_b32_e32 v51, 0xffff0000, v36
	v_lshl_add_u64 v[40:41], s[30:31], 0, v[40:41]
	v_pk_mul_f32 v[48:49], v[48:49], v[44:45] op_sel_hi:[1,0]
	v_lshl_add_u64 v[40:41], v[40:41], 0, s[6:7]
	v_cvt_pk_bf16_f32 v44, v48, v49
	v_lshlrev_b32_e32 v48, 9, v192
	v_add3_u32 v43, s74, v43, v48
	ds_write_b16 v43, v44
	ds_write_b16_d16_hi v43, v44 offset:64
	v_mov_b32_e32 v44, v45
	v_mov_b32_e32 v48, v82
	v_mov_b32_e32 v49, v98
	v_mov_b32_e32 v98, v83
	v_pk_mul_f32 v[44:45], v[96:97], v[44:45] op_sel_hi:[1,0]
	v_lshl_add_u64 v[40:41], v[40:41], 0, v[112:113]
	v_cvt_pk_bf16_f32 v44, v44, v45
	ds_write_b16 v43, v44 offset:128
	ds_write_b16_d16_hi v43, v44 offset:192
	v_mov_b32_e32 v44, v46
	s_andn2_b64 vcc, exec, s[60:61]
	s_mov_b64 s[34:35], 0
	v_pk_mul_f32 v[44:45], v[48:49], v[44:45] op_sel_hi:[1,0]
	s_nop 0
	v_cvt_pk_bf16_f32 v44, v44, v45
	ds_write_b16 v43, v44 offset:256
	ds_write_b16_d16_hi v43, v44 offset:320
	v_mov_b32_e32 v44, v47
	v_mov_b32_e32 v48, v84
	v_mov_b32_e32 v49, v100
	v_mov_b32_e32 v100, v85
	v_pk_mul_f32 v[44:45], v[98:99], v[44:45] op_sel_hi:[1,0]
	s_nop 0
	v_cvt_pk_bf16_f32 v44, v44, v45
	ds_write_b16 v43, v44 offset:384
	ds_write_b16_d16_hi v43, v44 offset:448
	ds_read_b128 v[44:47], v196 offset:160
	s_waitcnt lgkmcnt(0)
	s_nop 0
	v_pk_mul_f32 v[48:49], v[48:49], v[44:45] op_sel_hi:[1,0]
	s_nop 0
	v_cvt_pk_bf16_f32 v44, v48, v49
	ds_write_b16 v43, v44 offset:1024
	ds_write_b16_d16_hi v43, v44 offset:1088
	v_mov_b32_e32 v44, v45
	v_mov_b32_e32 v48, v86
	v_mov_b32_e32 v49, v102
	v_mov_b32_e32 v102, v87
	v_pk_mul_f32 v[44:45], v[100:101], v[44:45] op_sel_hi:[1,0]
	s_nop 0
	v_cvt_pk_bf16_f32 v44, v44, v45
	ds_write_b16 v43, v44 offset:1152
	ds_write_b16_d16_hi v43, v44 offset:1216
	v_mov_b32_e32 v44, v46
	s_nop 0
	v_pk_mul_f32 v[44:45], v[48:49], v[44:45] op_sel_hi:[1,0]
	s_nop 0
	v_cvt_pk_bf16_f32 v44, v44, v45
	ds_write_b16 v43, v44 offset:1280
	ds_write_b16_d16_hi v43, v44 offset:1344
	v_mov_b32_e32 v44, v47
	v_mov_b32_e32 v48, v88
	v_mov_b32_e32 v49, v104
	v_mov_b32_e32 v104, v89
	v_pk_mul_f32 v[44:45], v[102:103], v[44:45] op_sel_hi:[1,0]
	s_nop 0
	v_cvt_pk_bf16_f32 v44, v44, v45
	ds_write_b16 v43, v44 offset:1408
	ds_write_b16_d16_hi v43, v44 offset:1472
	ds_read_b128 v[44:47], v196 offset:192
	s_waitcnt lgkmcnt(0)
	s_nop 0
	v_pk_mul_f32 v[48:49], v[48:49], v[44:45] op_sel_hi:[1,0]
	s_nop 0
	v_cvt_pk_bf16_f32 v44, v48, v49
	ds_write_b16 v43, v44 offset:2048
	ds_write_b16_d16_hi v43, v44 offset:2112
	v_mov_b32_e32 v44, v45
	v_mov_b32_e32 v48, v90
	v_mov_b32_e32 v49, v106
	v_mov_b32_e32 v106, v91
	v_pk_mul_f32 v[44:45], v[104:105], v[44:45] op_sel_hi:[1,0]
	s_nop 0
	v_cvt_pk_bf16_f32 v44, v44, v45
	ds_write_b16 v43, v44 offset:2176
	ds_write_b16_d16_hi v43, v44 offset:2240
	v_mov_b32_e32 v44, v46
	s_nop 0
	v_pk_mul_f32 v[44:45], v[48:49], v[44:45] op_sel_hi:[1,0]
	s_nop 0
	v_cvt_pk_bf16_f32 v44, v44, v45
	ds_write_b16 v43, v44 offset:2304
	ds_write_b16_d16_hi v43, v44 offset:2368
	v_mov_b32_e32 v44, v47
	v_mov_b32_e32 v48, v92
	v_mov_b32_e32 v49, v108
	v_mov_b32_e32 v108, v93
	v_pk_mul_f32 v[44:45], v[106:107], v[44:45] op_sel_hi:[1,0]
	s_nop 0
	v_cvt_pk_bf16_f32 v44, v44, v45
	ds_write_b16 v43, v44 offset:2432
	ds_write_b16_d16_hi v43, v44 offset:2496
	ds_read_b128 v[44:47], v196 offset:224
	s_waitcnt lgkmcnt(0)
	s_nop 0
	v_pk_mul_f32 v[48:49], v[48:49], v[44:45] op_sel_hi:[1,0]
	s_nop 0
	v_cvt_pk_bf16_f32 v44, v48, v49
	ds_write_b16 v43, v44 offset:3072
	ds_write_b16_d16_hi v43, v44 offset:3136
	v_mov_b32_e32 v44, v45
	v_mov_b32_e32 v48, v94
	v_mov_b32_e32 v49, v110
	v_mov_b32_e32 v110, v95
	v_pk_mul_f32 v[44:45], v[108:109], v[44:45] op_sel_hi:[1,0]
	s_nop 0
	v_cvt_pk_bf16_f32 v44, v44, v45
	ds_write_b16 v43, v44 offset:3200
	ds_write_b16_d16_hi v43, v44 offset:3264
	v_mov_b32_e32 v44, v46
	s_nop 0
	v_pk_mul_f32 v[44:45], v[48:49], v[44:45] op_sel_hi:[1,0]
	s_nop 0
	v_cvt_pk_bf16_f32 v44, v44, v45
	ds_write_b16 v43, v44 offset:3328
	ds_write_b16_d16_hi v43, v44 offset:3392
	v_mov_b32_e32 v44, v47
	s_nop 0
	v_pk_mul_f32 v[44:45], v[110:111], v[44:45] op_sel_hi:[1,0]
	s_nop 0
	v_cvt_pk_bf16_f32 v44, v44, v45
	ds_write_b16 v43, v44 offset:3456
	ds_write_b16_d16_hi v43, v44 offset:3520
	v_add_u32_e32 v43, s74, v112
	s_waitcnt lgkmcnt(0)
	v_lshl_add_u32 v44, v42, 7, v43
	ds_read_b128 v[44:47], v44
	s_waitcnt lgkmcnt(0)
	v_lshlrev_b32_e32 v48, 16, v44
	v_and_b32_e32 v49, 0xffff0000, v44
	v_pk_mul_f32 v[48:49], v[50:51], v[48:49]
	v_lshlrev_b32_e32 v44, 16, v45
	v_cvt_pk_bf16_f32 v36, v48, v49
	v_and_b32_e32 v45, 0xffff0000, v45
	v_lshlrev_b32_e32 v48, 16, v37
	v_and_b32_e32 v49, 0xffff0000, v37
	v_pk_mul_f32 v[44:45], v[48:49], v[44:45]
	v_lshlrev_b32_e32 v48, 16, v38
	v_cvt_pk_bf16_f32 v37, v44, v45
	v_lshlrev_b32_e32 v44, 16, v46
	v_and_b32_e32 v45, 0xffff0000, v46
	v_and_b32_e32 v49, 0xffff0000, v38
	v_pk_mul_f32 v[44:45], v[48:49], v[44:45]
	v_lshlrev_b32_e32 v46, 16, v39
	v_cvt_pk_bf16_f32 v38, v44, v45
	v_lshlrev_b32_e32 v44, 16, v47
	v_and_b32_e32 v45, 0xffff0000, v47
	v_and_b32_e32 v47, 0xffff0000, v39
	v_pk_mul_f32 v[44:45], v[46:47], v[44:45]
	s_waitcnt vmcnt(2)
	v_lshlrev_b32_e32 v46, 16, v32
	v_cvt_pk_bf16_f32 v39, v44, v45
	global_store_dwordx4 v[40:41], v[36:39], off sc1
	s_nop 1
	v_add_u32_e32 v40, 8, v42
	v_lshl_add_u32 v36, v40, 7, v43
	ds_read_b128 v[36:39], v36
	v_and_b32_e32 v47, 0xffff0000, v32
	v_add_u32_e32 v40, s56, v40
	v_ashrrev_i32_e32 v41, 31, v40
	s_waitcnt lgkmcnt(0)
	v_lshlrev_b32_e32 v44, 16, v36
	v_and_b32_e32 v45, 0xffff0000, v36
	v_pk_mul_f32 v[44:45], v[46:47], v[44:45]
	v_lshlrev_b32_e32 v36, 16, v37
	v_cvt_pk_bf16_f32 v32, v44, v45
	v_and_b32_e32 v37, 0xffff0000, v37
	v_lshlrev_b32_e32 v44, 16, v33
	v_and_b32_e32 v45, 0xffff0000, v33
	v_pk_mul_f32 v[36:37], v[44:45], v[36:37]
	v_lshlrev_b32_e32 v44, 16, v34
	v_cvt_pk_bf16_f32 v33, v36, v37
	v_lshlrev_b32_e32 v36, 16, v38
	v_and_b32_e32 v37, 0xffff0000, v38
	v_and_b32_e32 v45, 0xffff0000, v34
	v_pk_mul_f32 v[36:37], v[44:45], v[36:37]
	v_lshlrev_b32_e32 v38, 16, v35
	v_cvt_pk_bf16_f32 v34, v36, v37
	v_lshlrev_b32_e32 v36, 16, v39
	v_and_b32_e32 v37, 0xffff0000, v39
	v_and_b32_e32 v39, 0xffff0000, v35
	v_pk_mul_f32 v[36:37], v[38:39], v[36:37]
	s_nop 0
	v_cvt_pk_bf16_f32 v35, v36, v37
	v_lshlrev_b64 v[36:37], 11, v[40:41]
	v_lshl_add_u64 v[36:37], s[30:31], 0, v[36:37]
	v_lshl_add_u64 v[36:37], v[36:37], 0, s[6:7]
	v_lshl_add_u64 v[36:37], v[36:37], 0, v[112:113]
	global_store_dwordx4 v[36:37], v[32:35], off sc1
	s_nop 1
	v_add_u32_e32 v36, 16, v42
	v_lshl_add_u32 v32, v36, 7, v43
	ds_read_b128 v[32:35], v32
	s_waitcnt vmcnt(3)
	v_lshlrev_b32_e32 v40, 16, v28
	v_and_b32_e32 v41, 0xffff0000, v28
	v_add_u32_e32 v36, s56, v36
	v_ashrrev_i32_e32 v37, 31, v36
	s_waitcnt lgkmcnt(0)
	v_lshlrev_b32_e32 v38, 16, v32
	v_and_b32_e32 v39, 0xffff0000, v32
	v_pk_mul_f32 v[38:39], v[40:41], v[38:39]
	v_lshlrev_b32_e32 v32, 16, v33
	v_cvt_pk_bf16_f32 v28, v38, v39
	v_and_b32_e32 v33, 0xffff0000, v33
	v_lshlrev_b32_e32 v38, 16, v29
	v_and_b32_e32 v39, 0xffff0000, v29
	v_pk_mul_f32 v[32:33], v[38:39], v[32:33]
	v_lshlrev_b32_e32 v38, 16, v30
	v_cvt_pk_bf16_f32 v29, v32, v33
	v_lshlrev_b32_e32 v32, 16, v34
	v_and_b32_e32 v33, 0xffff0000, v34
	v_and_b32_e32 v39, 0xffff0000, v30
	v_pk_mul_f32 v[32:33], v[38:39], v[32:33]
	v_lshlrev_b32_e32 v34, 16, v31
	v_cvt_pk_bf16_f32 v30, v32, v33
	v_lshlrev_b32_e32 v32, 16, v35
	v_and_b32_e32 v33, 0xffff0000, v35
	v_and_b32_e32 v35, 0xffff0000, v31
	v_pk_mul_f32 v[32:33], v[34:35], v[32:33]
	s_nop 0
	v_cvt_pk_bf16_f32 v31, v32, v33
	v_lshlrev_b64 v[32:33], 11, v[36:37]
	v_lshl_add_u64 v[32:33], s[30:31], 0, v[32:33]
	v_lshl_add_u64 v[32:33], v[32:33], 0, s[6:7]
	v_lshl_add_u64 v[32:33], v[32:33], 0, v[112:113]
	global_store_dwordx4 v[32:33], v[28:31], off sc1
	s_nop 1
	v_add_u32_e32 v32, 24, v42
	v_lshl_add_u32 v28, v32, 7, v43
	ds_read_b128 v[28:31], v28
	s_waitcnt vmcnt(3)
	v_lshlrev_b32_e32 v36, 16, v24
	v_and_b32_e32 v37, 0xffff0000, v24
	v_add_u32_e32 v32, s56, v32
	v_ashrrev_i32_e32 v33, 31, v32
	s_waitcnt lgkmcnt(0)
	v_lshlrev_b32_e32 v34, 16, v28
	v_and_b32_e32 v35, 0xffff0000, v28
	v_pk_mul_f32 v[34:35], v[36:37], v[34:35]
	v_lshlrev_b32_e32 v28, 16, v29
	v_cvt_pk_bf16_f32 v24, v34, v35
	v_and_b32_e32 v29, 0xffff0000, v29
	v_lshlrev_b32_e32 v34, 16, v25
	v_and_b32_e32 v35, 0xffff0000, v25
	v_pk_mul_f32 v[28:29], v[34:35], v[28:29]
	v_lshlrev_b32_e32 v34, 16, v26
	v_cvt_pk_bf16_f32 v25, v28, v29
	v_lshlrev_b32_e32 v28, 16, v30
	v_and_b32_e32 v29, 0xffff0000, v30
	v_and_b32_e32 v35, 0xffff0000, v26
	v_pk_mul_f32 v[28:29], v[34:35], v[28:29]
	v_lshlrev_b32_e32 v30, 16, v27
	v_cvt_pk_bf16_f32 v26, v28, v29
	v_lshlrev_b32_e32 v28, 16, v31
	v_and_b32_e32 v29, 0xffff0000, v31
	v_and_b32_e32 v31, 0xffff0000, v27
	v_pk_mul_f32 v[28:29], v[30:31], v[28:29]
	s_nop 0
	v_cvt_pk_bf16_f32 v27, v28, v29
	v_lshlrev_b64 v[28:29], 11, v[32:33]
	v_lshl_add_u64 v[28:29], s[30:31], 0, v[28:29]
	v_lshl_add_u64 v[28:29], v[28:29], 0, s[6:7]
	v_lshl_add_u64 v[28:29], v[28:29], 0, v[112:113]
	global_store_dwordx4 v[28:29], v[24:27], off sc1
	s_nop 1
	s_mov_b64 s[6:7], 0
	s_cbranch_vccnz .LBB0_1421
	s_waitcnt vmcnt(0) lgkmcnt(0)
	s_and_b64 s[34:35], s[4:5], exec

.LBB0_1503:
	s_movk_i32 s64, 0x2000
	v_rcp_f32_e32 v43, v43
	v_cmp_gt_u32_e32 vcc, 32, v188
	s_and_saveexec_b64 s[2:3], vcc
	v_lshl_add_u32 v44, v188, 2, s97
	ds_write_b32 v44, v43 offset:128
	s_or_b64 exec, exec, s[2:3]
	s_waitcnt lgkmcnt(0)
	ds_read_b128 v[44:47], v172 offset:128
	v_mov_b32_e32 v48, v80
	v_mov_b32_e32 v49, v96
	v_lshlrev_b32_e32 v43, 1, v193
	v_mov_b32_e32 v96, v81
	s_waitcnt lgkmcnt(0)
	s_waitcnt vmcnt(3)
	v_lshlrev_b32_e32 v50, 16, v36
	v_and_b32_e32 v51, 0xffff0000, v36
	v_lshl_add_u64 v[40:41], s[30:31], 0, v[40:41]
	v_pk_mul_f32 v[48:49], v[48:49], v[44:45] op_sel_hi:[1,0]
	v_lshl_add_u64 v[40:41], v[40:41], 0, s[4:5]
	v_cvt_pk_bf16_f32 v44, v48, v49
	v_lshlrev_b32_e32 v48, 9, v192
	v_add3_u32 v43, s74, v43, v48
	ds_write_b16 v43, v44
	ds_write_b16_d16_hi v43, v44 offset:64
	v_mov_b32_e32 v44, v45
	v_mov_b32_e32 v48, v82
	v_mov_b32_e32 v49, v98
	v_mov_b32_e32 v98, v83
	v_pk_mul_f32 v[44:45], v[96:97], v[44:45] op_sel_hi:[1,0]
	v_lshl_add_u64 v[40:41], v[40:41], 0, v[112:113]
	v_cvt_pk_bf16_f32 v44, v44, v45
	ds_write_b16 v43, v44 offset:128
	ds_write_b16_d16_hi v43, v44 offset:192
	v_mov_b32_e32 v44, v46
	s_andn2_b64 vcc, exec, s[60:61]
	v_pk_mul_f32 v[44:45], v[48:49], v[44:45] op_sel_hi:[1,0]
	s_nop 0
	v_cvt_pk_bf16_f32 v44, v44, v45
	ds_write_b16 v43, v44 offset:256
	ds_write_b16_d16_hi v43, v44 offset:320
	v_mov_b32_e32 v44, v47
	v_mov_b32_e32 v48, v84
	v_mov_b32_e32 v49, v100
	v_mov_b32_e32 v100, v85
	v_pk_mul_f32 v[44:45], v[98:99], v[44:45] op_sel_hi:[1,0]
	s_nop 0
	v_cvt_pk_bf16_f32 v44, v44, v45
	ds_write_b16 v43, v44 offset:384
	ds_write_b16_d16_hi v43, v44 offset:448
	ds_read_b128 v[44:47], v172 offset:160
	s_waitcnt lgkmcnt(0)
	s_nop 0
	v_pk_mul_f32 v[48:49], v[48:49], v[44:45] op_sel_hi:[1,0]
	s_nop 0
	v_cvt_pk_bf16_f32 v44, v48, v49
	ds_write_b16 v43, v44 offset:1024
	ds_write_b16_d16_hi v43, v44 offset:1088
	v_mov_b32_e32 v44, v45
	v_mov_b32_e32 v48, v86
	v_mov_b32_e32 v49, v102
	v_mov_b32_e32 v102, v87
	v_pk_mul_f32 v[44:45], v[100:101], v[44:45] op_sel_hi:[1,0]
	s_nop 0
	v_cvt_pk_bf16_f32 v44, v44, v45
	ds_write_b16 v43, v44 offset:1152
	ds_write_b16_d16_hi v43, v44 offset:1216
	v_mov_b32_e32 v44, v46
	s_nop 0
	v_pk_mul_f32 v[44:45], v[48:49], v[44:45] op_sel_hi:[1,0]
	s_nop 0
	v_cvt_pk_bf16_f32 v44, v44, v45
	ds_write_b16 v43, v44 offset:1280
	ds_write_b16_d16_hi v43, v44 offset:1344
	v_mov_b32_e32 v44, v47
	v_mov_b32_e32 v48, v88
	v_mov_b32_e32 v49, v104
	v_mov_b32_e32 v104, v89
	v_pk_mul_f32 v[44:45], v[102:103], v[44:45] op_sel_hi:[1,0]
	s_nop 0
	v_cvt_pk_bf16_f32 v44, v44, v45
	ds_write_b16 v43, v44 offset:1408
	ds_write_b16_d16_hi v43, v44 offset:1472
	ds_read_b128 v[44:47], v172 offset:192
	s_waitcnt lgkmcnt(0)
	s_nop 0
	v_pk_mul_f32 v[48:49], v[48:49], v[44:45] op_sel_hi:[1,0]
	s_nop 0
	v_cvt_pk_bf16_f32 v44, v48, v49
	ds_write_b16 v43, v44 offset:2048
	ds_write_b16_d16_hi v43, v44 offset:2112
	v_mov_b32_e32 v44, v45
	v_mov_b32_e32 v48, v90
	v_mov_b32_e32 v49, v106
	v_mov_b32_e32 v106, v91
	v_pk_mul_f32 v[44:45], v[104:105], v[44:45] op_sel_hi:[1,0]
	s_nop 0
	v_cvt_pk_bf16_f32 v44, v44, v45
	ds_write_b16 v43, v44 offset:2176
	ds_write_b16_d16_hi v43, v44 offset:2240
	v_mov_b32_e32 v44, v46
	s_nop 0
	v_pk_mul_f32 v[44:45], v[48:49], v[44:45] op_sel_hi:[1,0]
	s_nop 0
	v_cvt_pk_bf16_f32 v44, v44, v45
	ds_write_b16 v43, v44 offset:2304
	ds_write_b16_d16_hi v43, v44 offset:2368
	v_mov_b32_e32 v44, v47
	v_mov_b32_e32 v48, v92
	v_mov_b32_e32 v49, v108
	v_mov_b32_e32 v108, v93
	v_pk_mul_f32 v[44:45], v[106:107], v[44:45] op_sel_hi:[1,0]
	s_nop 0
	v_cvt_pk_bf16_f32 v44, v44, v45
	ds_write_b16 v43, v44 offset:2432
	ds_write_b16_d16_hi v43, v44 offset:2496
	ds_read_b128 v[44:47], v172 offset:224
	s_waitcnt lgkmcnt(0)
	s_nop 0
	v_pk_mul_f32 v[48:49], v[48:49], v[44:45] op_sel_hi:[1,0]
	s_nop 0
	v_cvt_pk_bf16_f32 v44, v48, v49
	ds_write_b16 v43, v44 offset:3072
	ds_write_b16_d16_hi v43, v44 offset:3136
	v_mov_b32_e32 v44, v45
	v_mov_b32_e32 v48, v94
	v_mov_b32_e32 v49, v110
	v_mov_b32_e32 v110, v95
	v_pk_mul_f32 v[44:45], v[108:109], v[44:45] op_sel_hi:[1,0]
	s_nop 0
	v_cvt_pk_bf16_f32 v44, v44, v45
	ds_write_b16 v43, v44 offset:3200
	ds_write_b16_d16_hi v43, v44 offset:3264
	v_mov_b32_e32 v44, v46
	s_nop 0
	v_pk_mul_f32 v[44:45], v[48:49], v[44:45] op_sel_hi:[1,0]
	s_nop 0
	v_cvt_pk_bf16_f32 v44, v44, v45
	ds_write_b16 v43, v44 offset:3328
	ds_write_b16_d16_hi v43, v44 offset:3392
	v_mov_b32_e32 v44, v47
	s_nop 0
	v_pk_mul_f32 v[44:45], v[110:111], v[44:45] op_sel_hi:[1,0]
	s_nop 0
	v_cvt_pk_bf16_f32 v44, v44, v45
	ds_write_b16 v43, v44 offset:3456
	ds_write_b16_d16_hi v43, v44 offset:3520
	v_add_u32_e32 v43, s74, v112
	s_waitcnt lgkmcnt(0)
	v_lshl_add_u32 v44, v42, 7, v43
	ds_read_b128 v[44:47], v44
	s_waitcnt lgkmcnt(0)
	v_lshlrev_b32_e32 v48, 16, v44
	v_and_b32_e32 v49, 0xffff0000, v44
	v_pk_mul_f32 v[48:49], v[50:51], v[48:49]
	v_lshlrev_b32_e32 v44, 16, v45
	v_cvt_pk_bf16_f32 v36, v48, v49
	v_and_b32_e32 v45, 0xffff0000, v45
	v_lshlrev_b32_e32 v48, 16, v37
	v_and_b32_e32 v49, 0xffff0000, v37
	v_pk_mul_f32 v[44:45], v[48:49], v[44:45]
	v_lshlrev_b32_e32 v48, 16, v38
	v_cvt_pk_bf16_f32 v37, v44, v45
	v_lshlrev_b32_e32 v44, 16, v46
	v_and_b32_e32 v45, 0xffff0000, v46
	v_and_b32_e32 v49, 0xffff0000, v38
	v_pk_mul_f32 v[44:45], v[48:49], v[44:45]
	v_lshlrev_b32_e32 v46, 16, v39
	v_cvt_pk_bf16_f32 v38, v44, v45
	v_lshlrev_b32_e32 v44, 16, v47
	v_and_b32_e32 v45, 0xffff0000, v47
	v_and_b32_e32 v47, 0xffff0000, v39
	v_pk_mul_f32 v[44:45], v[46:47], v[44:45]
	s_waitcnt vmcnt(2)
	v_lshlrev_b32_e32 v46, 16, v32
	v_cvt_pk_bf16_f32 v39, v44, v45
	global_store_dwordx4 v[40:41], v[36:39], off sc1
	s_nop 1
	v_add_u32_e32 v40, 8, v42
	v_lshl_add_u32 v36, v40, 7, v43
	ds_read_b128 v[36:39], v36
	v_and_b32_e32 v47, 0xffff0000, v32
	v_add_u32_e32 v40, s56, v40
	v_ashrrev_i32_e32 v41, 31, v40
	s_waitcnt lgkmcnt(0)
	v_lshlrev_b32_e32 v44, 16, v36
	v_and_b32_e32 v45, 0xffff0000, v36
	v_pk_mul_f32 v[44:45], v[46:47], v[44:45]
	v_lshlrev_b32_e32 v36, 16, v37
	v_cvt_pk_bf16_f32 v32, v44, v45
	v_and_b32_e32 v37, 0xffff0000, v37
	v_lshlrev_b32_e32 v44, 16, v33
	v_and_b32_e32 v45, 0xffff0000, v33
	v_pk_mul_f32 v[36:37], v[44:45], v[36:37]
	v_lshlrev_b32_e32 v44, 16, v34
	v_cvt_pk_bf16_f32 v33, v36, v37
	v_lshlrev_b32_e32 v36, 16, v38
	v_and_b32_e32 v37, 0xffff0000, v38
	v_and_b32_e32 v45, 0xffff0000, v34
	v_pk_mul_f32 v[36:37], v[44:45], v[36:37]
	v_lshlrev_b32_e32 v38, 16, v35
	v_cvt_pk_bf16_f32 v34, v36, v37
	v_lshlrev_b32_e32 v36, 16, v39
	v_and_b32_e32 v37, 0xffff0000, v39
	v_and_b32_e32 v39, 0xffff0000, v35
	v_pk_mul_f32 v[36:37], v[38:39], v[36:37]
	s_nop 0
	v_cvt_pk_bf16_f32 v35, v36, v37
	v_lshlrev_b64 v[36:37], 11, v[40:41]
	v_lshl_add_u64 v[36:37], s[30:31], 0, v[36:37]
	v_lshl_add_u64 v[36:37], v[36:37], 0, s[4:5]
	v_lshl_add_u64 v[36:37], v[36:37], 0, v[112:113]
	global_store_dwordx4 v[36:37], v[32:35], off sc1
	s_nop 1
	v_add_u32_e32 v36, 16, v42
	v_lshl_add_u32 v32, v36, 7, v43
	ds_read_b128 v[32:35], v32
	s_waitcnt vmcnt(3)
	v_lshlrev_b32_e32 v40, 16, v28
	v_and_b32_e32 v41, 0xffff0000, v28
	v_add_u32_e32 v36, s56, v36
	v_ashrrev_i32_e32 v37, 31, v36
	s_waitcnt lgkmcnt(0)
	v_lshlrev_b32_e32 v38, 16, v32
	v_and_b32_e32 v39, 0xffff0000, v32
	v_pk_mul_f32 v[38:39], v[40:41], v[38:39]
	v_lshlrev_b32_e32 v32, 16, v33
	v_cvt_pk_bf16_f32 v28, v38, v39
	v_and_b32_e32 v33, 0xffff0000, v33
	v_lshlrev_b32_e32 v38, 16, v29
	v_and_b32_e32 v39, 0xffff0000, v29
	v_pk_mul_f32 v[32:33], v[38:39], v[32:33]
	v_lshlrev_b32_e32 v38, 16, v30
	v_cvt_pk_bf16_f32 v29, v32, v33
	v_lshlrev_b32_e32 v32, 16, v34
	v_and_b32_e32 v33, 0xffff0000, v34
	v_and_b32_e32 v39, 0xffff0000, v30
	v_pk_mul_f32 v[32:33], v[38:39], v[32:33]
	v_lshlrev_b32_e32 v34, 16, v31
	v_cvt_pk_bf16_f32 v30, v32, v33
	v_lshlrev_b32_e32 v32, 16, v35
	v_and_b32_e32 v33, 0xffff0000, v35
	v_and_b32_e32 v35, 0xffff0000, v31
	v_pk_mul_f32 v[32:33], v[34:35], v[32:33]
	s_nop 0
	v_cvt_pk_bf16_f32 v31, v32, v33
	v_lshlrev_b64 v[32:33], 11, v[36:37]
	v_lshl_add_u64 v[32:33], s[30:31], 0, v[32:33]
	v_lshl_add_u64 v[32:33], v[32:33], 0, s[4:5]
	v_lshl_add_u64 v[32:33], v[32:33], 0, v[112:113]
	global_store_dwordx4 v[32:33], v[28:31], off sc1
	s_nop 1
	v_add_u32_e32 v32, 24, v42
	v_lshl_add_u32 v28, v32, 7, v43
	ds_read_b128 v[28:31], v28
	s_waitcnt vmcnt(3)
	v_lshlrev_b32_e32 v36, 16, v24
	v_and_b32_e32 v37, 0xffff0000, v24
	v_add_u32_e32 v32, s56, v32
	v_ashrrev_i32_e32 v33, 31, v32
	s_waitcnt lgkmcnt(0)
	v_lshlrev_b32_e32 v34, 16, v28
	v_and_b32_e32 v35, 0xffff0000, v28
	v_pk_mul_f32 v[34:35], v[36:37], v[34:35]
	v_lshlrev_b32_e32 v28, 16, v29
	v_cvt_pk_bf16_f32 v24, v34, v35
	v_and_b32_e32 v29, 0xffff0000, v29
	v_lshlrev_b32_e32 v34, 16, v25
	v_and_b32_e32 v35, 0xffff0000, v25
	v_pk_mul_f32 v[28:29], v[34:35], v[28:29]
	v_lshlrev_b32_e32 v34, 16, v26
	v_cvt_pk_bf16_f32 v25, v28, v29
	v_lshlrev_b32_e32 v28, 16, v30
	v_and_b32_e32 v29, 0xffff0000, v30
	v_and_b32_e32 v35, 0xffff0000, v26
	v_pk_mul_f32 v[28:29], v[34:35], v[28:29]
	v_lshlrev_b32_e32 v30, 16, v27
	v_cvt_pk_bf16_f32 v26, v28, v29
	v_lshlrev_b32_e32 v28, 16, v31
	v_and_b32_e32 v29, 0xffff0000, v31
	v_and_b32_e32 v31, 0xffff0000, v27
	v_pk_mul_f32 v[28:29], v[30:31], v[28:29]
	s_nop 0
	v_cvt_pk_bf16_f32 v27, v28, v29
	v_lshlrev_b64 v[28:29], 11, v[32:33]
	v_lshl_add_u64 v[28:29], s[30:31], 0, v[28:29]
	v_lshl_add_u64 v[28:29], v[28:29], 0, s[4:5]
	v_lshl_add_u64 v[28:29], v[28:29], 0, v[112:113]
	global_store_dwordx4 v[28:29], v[24:27], off sc1
	s_nop 1
	s_cbranch_vccnz .LBB0_1507
	s_waitcnt vmcnt(0) lgkmcnt(0)
	s_andn2_b64 s[2:3], s[34:35], exec
	s_and_b64 s[4:5], s[10:11], exec
	s_or_b64 s[34:35], s[2:3], s[4:5]
